# residual-epilogue GEMMs: units after the first skip the two leading vmcnt waits of the peeled K iteration (their K-tiles landed before the previous epilogue's vmcnt(0)); no wait on the epilogue's stor
# baseline (speedup 1.0000x reference)
.LBB0_594:
	s_ashr_i32 s81, s80, 31
	s_lshl_b64 s[84:85], s[80:81], 20
	s_add_u32 s84, s29, s84
	s_addc_u32 s85, s34, s85
	s_and_b64 s[86:87], s[82:83], exec
	s_cselect_b32 s81, s85, s95
	s_cselect_b32 vcc_lo, s84, s94
	s_ashr_i32 s79, s78, 31
	s_lshl_b64 s[86:87], s[78:79], 20
	s_add_u32 s86, s35, s86
	s_addc_u32 s87, s38, s87
	s_and_b64 s[2:3], s[82:83], exec
	s_cselect_b32 s79, s87, s93
	s_cselect_b32 vcc_hi, s86, s92
	s_lshl_b32 s88, s88, 8
	s_ashr_i32 s89, s88, 31
	s_lshl_b64 s[2:3], s[88:89], 2
	s_add_u32 s2, s90, s2
	s_addc_u32 s3, s91, s3
	s_add_i32 m0, s14, s41
	s_add_u32 s90, s94, 0x80080
	global_load_lds_dwordx4 v239, s[2:3]
	s_addc_u32 s91, s95, 0
	s_add_u32 s89, s92, 0x100
	s_addc_u32 s14, s93, 0
	s_mov_b32 s20, -2
	s_waitcnt vmcnt(0)
	s_add_u32 s2, s90, 0xfff80080
	s_addc_u32 s3, s91, -1
	s_add_i32 s67, 0, 0x10000
	s_cmp_eq_u32 s20, 28
	s_cselect_b32 s95, s81, s3
	s_cselect_b32 s94, vcc_lo, s2
	s_cselect_b32 s93, s79, s14
	s_cselect_b32 s92, vcc_hi, s89
	s_add_i32 s76, 0, 0x14000
	v_add_u32_e32 v96, s67, v238
	v_add_u32_e32 v140, s76, v238
	ds_read_b128 v[64:67], v96
	ds_read_b128 v[72:75], v96 offset:1024
	ds_read_b128 v[88:91], v96 offset:2048
	ds_read_b128 v[96:99], v96 offset:3072
	ds_read_b128 v[108:111], v140
	ds_read_b128 v[116:119], v140 offset:1024
	ds_read_b128 v[128:131], v140 offset:2048
	ds_read_b128 v[140:143], v140 offset:3072
	s_add_i32 m0, s39, 0xc000
	ds_read_b128 v[152:155], v240
	ds_read_b128 v[156:159], v240 offset:1024
	ds_read_b128 v[160:163], v240 offset:2048
	ds_read_b128 v[164:167], v240 offset:3072
	ds_read_b128 v[168:171], v240 offset:4096
	ds_read_b128 v[180:183], v240 offset:5120
	ds_read_b128 v[184:187], v240 offset:6144
	ds_read_b128 v[188:191], v240 offset:7168
	global_load_lds_dwordx4 v230, s[90:91]
	s_add_i32 m0, s39, 0xe000
	s_nop 0
	global_load_lds_dwordx4 v232, s[90:91]
	s_cmp_lg_u32 s54, 1
	s_cbranch_scc1 .Lds2_0
	s_waitcnt vmcnt(8)
.Lds2_0:
	s_waitcnt lgkmcnt(0)
	s_barrier
	s_waitcnt lgkmcnt(0)
	v_mfma_f32_16x16x32_bf16 v[176:179], v[64:67], v[152:155], 0
	v_mfma_f32_16x16x32_bf16 v[176:179], v[72:75], v[156:159], v[176:179]
	v_mfma_f32_16x16x32_bf16 v[148:151], v[108:111], v[152:155], 0
	v_mfma_f32_16x16x32_bf16 v[148:151], v[116:119], v[156:159], v[148:151]
	v_mfma_f32_16x16x32_bf16 v[172:175], v[88:91], v[152:155], 0
	v_mfma_f32_16x16x32_bf16 v[172:175], v[96:99], v[156:159], v[172:175]
	v_mfma_f32_16x16x32_bf16 v[144:147], v[128:131], v[152:155], 0
	v_mfma_f32_16x16x32_bf16 v[144:147], v[140:143], v[156:159], v[144:147]
	v_mfma_f32_16x16x32_bf16 v[136:139], v[64:67], v[160:163], 0
	v_mfma_f32_16x16x32_bf16 v[136:139], v[72:75], v[164:167], v[136:139]
	v_mfma_f32_16x16x32_bf16 v[124:127], v[108:111], v[160:163], 0
	v_mfma_f32_16x16x32_bf16 v[124:127], v[116:119], v[164:167], v[124:127]
	v_mfma_f32_16x16x32_bf16 v[132:135], v[88:91], v[160:163], 0
	v_mfma_f32_16x16x32_bf16 v[132:135], v[96:99], v[164:167], v[132:135]
	v_mfma_f32_16x16x32_bf16 v[120:123], v[128:131], v[160:163], 0
	v_mfma_f32_16x16x32_bf16 v[120:123], v[140:143], v[164:167], v[120:123]
	v_mfma_f32_16x16x32_bf16 v[112:115], v[64:67], v[168:171], 0
	v_mfma_f32_16x16x32_bf16 v[112:115], v[72:75], v[180:183], v[112:115]
	v_mfma_f32_16x16x32_bf16 v[100:103], v[108:111], v[168:171], 0
	v_mfma_f32_16x16x32_bf16 v[100:103], v[116:119], v[180:183], v[100:103]
	v_mfma_f32_16x16x32_bf16 v[104:107], v[88:91], v[168:171], 0
	v_mfma_f32_16x16x32_bf16 v[104:107], v[96:99], v[180:183], v[104:107]
	v_mfma_f32_16x16x32_bf16 v[92:95], v[128:131], v[168:171], 0
	v_mfma_f32_16x16x32_bf16 v[92:95], v[140:143], v[180:183], v[92:95]
	v_mfma_f32_16x16x32_bf16 v[84:87], v[64:67], v[184:187], 0
	v_mfma_f32_16x16x32_bf16 v[84:87], v[72:75], v[188:191], v[84:87]
	v_mfma_f32_16x16x32_bf16 v[76:79], v[108:111], v[184:187], 0
	v_mfma_f32_16x16x32_bf16 v[76:79], v[116:119], v[188:191], v[76:79]
	v_mfma_f32_16x16x32_bf16 v[80:83], v[88:91], v[184:187], 0
	v_mfma_f32_16x16x32_bf16 v[80:83], v[96:99], v[188:191], v[80:83]
	v_mfma_f32_16x16x32_bf16 v[68:71], v[128:131], v[184:187], 0
	v_mfma_f32_16x16x32_bf16 v[68:71], v[140:143], v[188:191], v[68:71]
	s_barrier
	s_add_i32 s2, s67, s28
	s_mov_b32 m0, s2
	ds_read_b128 v[152:155], v240 offset:16384
	ds_read_b128 v[156:159], v240 offset:17408
	ds_read_b128 v[160:163], v240 offset:18432
	ds_read_b128 v[164:167], v240 offset:19456
	ds_read_b128 v[168:171], v240 offset:20480
	ds_read_b128 v[180:183], v240 offset:21504
	ds_read_b128 v[184:187], v240 offset:22528
	ds_read_b128 v[188:191], v240 offset:23552
	global_load_lds_dwordx4 v216, s[92:93]
	s_add_i32 m0, s2, 0x2000
	s_add_u32 s2, s92, 0x80000
	s_addc_u32 s3, s93, 0
	s_add_i32 s67, s76, s28
	global_load_lds_dwordx4 v228, s[92:93]
	s_mov_b32 m0, s67
	s_nop 0
	global_load_lds_dwordx4 v216, s[2:3]
	s_add_i32 m0, s67, 0x2000
	s_nop 0
	global_load_lds_dwordx4 v228, s[2:3]
	s_mov_b32 m0, s39
	s_nop 0
	global_load_lds_dwordx4 v224, s[94:95]
	s_mov_b32 m0, s53
	s_nop 0
	global_load_lds_dwordx4 v226, s[94:95]
	s_cmp_lg_u32 s54, 1
	s_cbranch_scc1 .Lds2_1
	s_waitcnt vmcnt(8)
.Lds2_1:
	s_waitcnt lgkmcnt(0)
	s_barrier
	s_waitcnt lgkmcnt(0)
	v_mfma_f32_16x16x32_bf16 v[60:63], v[64:67], v[152:155], 0
	v_mfma_f32_16x16x32_bf16 v[60:63], v[72:75], v[156:159], v[60:63]
	v_mfma_f32_16x16x32_bf16 v[52:55], v[108:111], v[152:155], 0
	v_mfma_f32_16x16x32_bf16 v[52:55], v[116:119], v[156:159], v[52:55]
	v_mfma_f32_16x16x32_bf16 v[56:59], v[88:91], v[152:155], 0
	v_mfma_f32_16x16x32_bf16 v[56:59], v[96:99], v[156:159], v[56:59]
	v_mfma_f32_16x16x32_bf16 v[48:51], v[128:131], v[152:155], 0
	v_mfma_f32_16x16x32_bf16 v[48:51], v[140:143], v[156:159], v[48:51]
	v_mfma_f32_16x16x32_bf16 v[44:47], v[64:67], v[160:163], 0
	v_mfma_f32_16x16x32_bf16 v[44:47], v[72:75], v[164:167], v[44:47]
	v_mfma_f32_16x16x32_bf16 v[36:39], v[108:111], v[160:163], 0
	v_mfma_f32_16x16x32_bf16 v[36:39], v[116:119], v[164:167], v[36:39]
	v_mfma_f32_16x16x32_bf16 v[40:43], v[88:91], v[160:163], 0
	v_mfma_f32_16x16x32_bf16 v[40:43], v[96:99], v[164:167], v[40:43]
	v_mfma_f32_16x16x32_bf16 v[32:35], v[128:131], v[160:163], 0
	v_mfma_f32_16x16x32_bf16 v[32:35], v[140:143], v[164:167], v[32:35]
	v_mfma_f32_16x16x32_bf16 v[28:31], v[64:67], v[168:171], 0
	v_mfma_f32_16x16x32_bf16 v[28:31], v[72:75], v[180:183], v[28:31]
	v_mfma_f32_16x16x32_bf16 v[20:23], v[108:111], v[168:171], 0
	v_mfma_f32_16x16x32_bf16 v[20:23], v[116:119], v[180:183], v[20:23]
	v_mfma_f32_16x16x32_bf16 v[24:27], v[88:91], v[168:171], 0
	v_mfma_f32_16x16x32_bf16 v[24:27], v[96:99], v[180:183], v[24:27]
	v_mfma_f32_16x16x32_bf16 v[16:19], v[128:131], v[168:171], 0
	v_mfma_f32_16x16x32_bf16 v[16:19], v[140:143], v[180:183], v[16:19]
	v_mfma_f32_16x16x32_bf16 v[12:15], v[64:67], v[184:187], 0
	v_mfma_f32_16x16x32_bf16 v[12:15], v[72:75], v[188:191], v[12:15]
	v_mfma_f32_16x16x32_bf16 v[4:7], v[108:111], v[184:187], 0
	v_mfma_f32_16x16x32_bf16 v[4:7], v[116:119], v[188:191], v[4:7]
	v_mfma_f32_16x16x32_bf16 v[8:11], v[88:91], v[184:187], 0
	v_mfma_f32_16x16x32_bf16 v[8:11], v[96:99], v[188:191], v[8:11]
	v_mfma_f32_16x16x32_bf16 v[0:3], v[128:131], v[184:187], 0
	v_mfma_f32_16x16x32_bf16 v[0:3], v[140:143], v[188:191], v[0:3]
	s_barrier
	s_add_i32 s67, 0, 0x18000
	s_add_i32 s76, 0, 0x1c000
	v_add_u32_e32 v96, s67, v238
	v_add_u32_e32 v140, s76, v238
	ds_read_b128 v[64:67], v96
	ds_read_b128 v[72:75], v96 offset:1024
	ds_read_b128 v[88:91], v96 offset:2048
	ds_read_b128 v[96:99], v96 offset:3072
	ds_read_b128 v[108:111], v140
	ds_read_b128 v[116:119], v140 offset:1024
	ds_read_b128 v[128:131], v140 offset:2048
	ds_read_b128 v[140:143], v140 offset:3072
	s_add_u32 s2, s94, 0x80000
	s_addc_u32 s3, s95, 0
	s_mov_b32 m0, s55
	ds_read_b128 v[152:155], v240 offset:32768
	ds_read_b128 v[156:159], v240 offset:33792
	ds_read_b128 v[160:163], v240 offset:34816
	ds_read_b128 v[164:167], v240 offset:35840
	ds_read_b128 v[168:171], v240 offset:36864
	ds_read_b128 v[180:183], v240 offset:37888
	ds_read_b128 v[184:187], v240 offset:38912
	ds_read_b128 v[188:191], v240 offset:39936
	global_load_lds_dwordx4 v224, s[2:3]
	s_mov_b32 m0, s56
	s_nop 0
	global_load_lds_dwordx4 v226, s[2:3]
	s_waitcnt vmcnt(8)
	s_waitcnt lgkmcnt(0)
	s_barrier
	s_waitcnt lgkmcnt(0)
	v_mfma_f32_16x16x32_bf16 v[176:179], v[64:67], v[152:155], v[176:179]
	v_mfma_f32_16x16x32_bf16 v[176:179], v[72:75], v[156:159], v[176:179]
	v_mfma_f32_16x16x32_bf16 v[148:151], v[108:111], v[152:155], v[148:151]
	v_mfma_f32_16x16x32_bf16 v[148:151], v[116:119], v[156:159], v[148:151]
	v_mfma_f32_16x16x32_bf16 v[172:175], v[88:91], v[152:155], v[172:175]
	v_mfma_f32_16x16x32_bf16 v[172:175], v[96:99], v[156:159], v[172:175]
	v_mfma_f32_16x16x32_bf16 v[144:147], v[128:131], v[152:155], v[144:147]
	v_mfma_f32_16x16x32_bf16 v[144:147], v[140:143], v[156:159], v[144:147]
	v_mfma_f32_16x16x32_bf16 v[136:139], v[64:67], v[160:163], v[136:139]
	v_mfma_f32_16x16x32_bf16 v[136:139], v[72:75], v[164:167], v[136:139]
	v_mfma_f32_16x16x32_bf16 v[124:127], v[108:111], v[160:163], v[124:127]
	v_mfma_f32_16x16x32_bf16 v[124:127], v[116:119], v[164:167], v[124:127]
	v_mfma_f32_16x16x32_bf16 v[132:135], v[88:91], v[160:163], v[132:135]
	v_mfma_f32_16x16x32_bf16 v[132:135], v[96:99], v[164:167], v[132:135]
	v_mfma_f32_16x16x32_bf16 v[120:123], v[128:131], v[160:163], v[120:123]
	v_mfma_f32_16x16x32_bf16 v[120:123], v[140:143], v[164:167], v[120:123]
	v_mfma_f32_16x16x32_bf16 v[112:115], v[64:67], v[168:171], v[112:115]
	v_mfma_f32_16x16x32_bf16 v[112:115], v[72:75], v[180:183], v[112:115]
	v_mfma_f32_16x16x32_bf16 v[100:103], v[108:111], v[168:171], v[100:103]
	v_mfma_f32_16x16x32_bf16 v[100:103], v[116:119], v[180:183], v[100:103]
	v_mfma_f32_16x16x32_bf16 v[104:107], v[88:91], v[168:171], v[104:107]
	v_mfma_f32_16x16x32_bf16 v[104:107], v[96:99], v[180:183], v[104:107]
	v_mfma_f32_16x16x32_bf16 v[92:95], v[128:131], v[168:171], v[92:95]
	v_mfma_f32_16x16x32_bf16 v[92:95], v[140:143], v[180:183], v[92:95]
	v_mfma_f32_16x16x32_bf16 v[84:87], v[64:67], v[184:187], v[84:87]
	v_mfma_f32_16x16x32_bf16 v[84:87], v[72:75], v[188:191], v[84:87]
	v_mfma_f32_16x16x32_bf16 v[76:79], v[108:111], v[184:187], v[76:79]
	v_mfma_f32_16x16x32_bf16 v[76:79], v[116:119], v[188:191], v[76:79]
	v_mfma_f32_16x16x32_bf16 v[80:83], v[88:91], v[184:187], v[80:83]
	v_mfma_f32_16x16x32_bf16 v[80:83], v[96:99], v[188:191], v[80:83]
	v_mfma_f32_16x16x32_bf16 v[68:71], v[128:131], v[184:187], v[68:71]
	v_mfma_f32_16x16x32_bf16 v[68:71], v[140:143], v[188:191], v[68:71]
	s_barrier
	s_add_i32 s2, s67, s28
	s_add_u32 s98, s92, 0x80
	s_addc_u32 s99, s93, 0
	s_mov_b32 m0, s2
	ds_read_b128 v[152:155], v240 offset:49152
	ds_read_b128 v[156:159], v240 offset:50176
	ds_read_b128 v[160:163], v240 offset:51200
	ds_read_b128 v[164:167], v240 offset:52224
	ds_read_b128 v[168:171], v240 offset:53248
	ds_read_b128 v[180:183], v240 offset:54272
	ds_read_b128 v[184:187], v240 offset:55296
	ds_read_b128 v[188:191], v240 offset:56320
	global_load_lds_dwordx4 v216, s[98:99]
	s_add_i32 m0, s2, 0x2000
	s_add_u32 s2, s92, 0x80080
	s_addc_u32 s3, s93, 0
	s_add_i32 s67, s76, s28
	global_load_lds_dwordx4 v228, s[98:99]
	s_mov_b32 m0, s67
	s_nop 0
	global_load_lds_dwordx4 v216, s[2:3]
	s_add_i32 m0, s67, 0x2000
	s_nop 0
	global_load_lds_dwordx4 v228, s[2:3]
	s_add_u32 s98, s94, 0x80
	s_addc_u32 s99, s95, 0
	s_mov_b32 m0, s70
	s_nop 0
	global_load_lds_dwordx4 v224, s[98:99]
	s_mov_b32 m0, s71
	s_nop 0
	global_load_lds_dwordx4 v226, s[98:99]
	s_waitcnt vmcnt(8)
	s_waitcnt lgkmcnt(0)
	s_barrier
	s_waitcnt lgkmcnt(0)
	v_mfma_f32_16x16x32_bf16 v[60:63], v[64:67], v[152:155], v[60:63]
	v_mfma_f32_16x16x32_bf16 v[60:63], v[72:75], v[156:159], v[60:63]
	v_mfma_f32_16x16x32_bf16 v[52:55], v[108:111], v[152:155], v[52:55]
	v_mfma_f32_16x16x32_bf16 v[52:55], v[116:119], v[156:159], v[52:55]
	v_mfma_f32_16x16x32_bf16 v[56:59], v[88:91], v[152:155], v[56:59]
	v_mfma_f32_16x16x32_bf16 v[56:59], v[96:99], v[156:159], v[56:59]
	v_mfma_f32_16x16x32_bf16 v[48:51], v[128:131], v[152:155], v[48:51]
	v_mfma_f32_16x16x32_bf16 v[48:51], v[140:143], v[156:159], v[48:51]
	v_mfma_f32_16x16x32_bf16 v[44:47], v[64:67], v[160:163], v[44:47]
	v_mfma_f32_16x16x32_bf16 v[44:47], v[72:75], v[164:167], v[44:47]
	v_mfma_f32_16x16x32_bf16 v[36:39], v[108:111], v[160:163], v[36:39]
	v_mfma_f32_16x16x32_bf16 v[36:39], v[116:119], v[164:167], v[36:39]
	v_mfma_f32_16x16x32_bf16 v[40:43], v[88:91], v[160:163], v[40:43]
	v_mfma_f32_16x16x32_bf16 v[40:43], v[96:99], v[164:167], v[40:43]
	v_mfma_f32_16x16x32_bf16 v[32:35], v[128:131], v[160:163], v[32:35]
	v_mfma_f32_16x16x32_bf16 v[32:35], v[140:143], v[164:167], v[32:35]
	v_mfma_f32_16x16x32_bf16 v[28:31], v[64:67], v[168:171], v[28:31]
	v_mfma_f32_16x16x32_bf16 v[28:31], v[72:75], v[180:183], v[28:31]
	v_mfma_f32_16x16x32_bf16 v[20:23], v[108:111], v[168:171], v[20:23]
	v_mfma_f32_16x16x32_bf16 v[20:23], v[116:119], v[180:183], v[20:23]
	v_mfma_f32_16x16x32_bf16 v[24:27], v[88:91], v[168:171], v[24:27]
	v_mfma_f32_16x16x32_bf16 v[24:27], v[96:99], v[180:183], v[24:27]
	v_mfma_f32_16x16x32_bf16 v[16:19], v[128:131], v[168:171], v[16:19]
	v_mfma_f32_16x16x32_bf16 v[16:19], v[140:143], v[180:183], v[16:19]
	v_mfma_f32_16x16x32_bf16 v[12:15], v[64:67], v[184:187], v[12:15]
	v_mfma_f32_16x16x32_bf16 v[12:15], v[72:75], v[188:191], v[12:15]
	v_mfma_f32_16x16x32_bf16 v[4:7], v[108:111], v[184:187], v[4:7]
	v_mfma_f32_16x16x32_bf16 v[4:7], v[116:119], v[188:191], v[4:7]
	v_mfma_f32_16x16x32_bf16 v[8:11], v[88:91], v[184:187], v[8:11]
	v_mfma_f32_16x16x32_bf16 v[8:11], v[96:99], v[188:191], v[8:11]
	v_mfma_f32_16x16x32_bf16 v[0:3], v[128:131], v[184:187], v[0:3]
	v_mfma_f32_16x16x32_bf16 v[0:3], v[140:143], v[188:191], v[0:3]
	s_barrier
	s_add_i32 s20, s20, 2
	s_add_u32 s90, s90, 0x100
	s_addc_u32 s91, s91, 0
	s_add_u32 s89, s89, 0x100
	s_addc_u32 s14, s14, 0

.LBB0_964:
	s_ashr_i32 s79, s78, 31
	s_lshl_b64 s[82:83], s[78:79], 20
	s_add_u32 s82, s14, s82
	s_addc_u32 s83, s15, s83
	s_and_b64 s[84:85], s[80:81], exec
	s_cselect_b32 s79, s83, s93
	s_cselect_b32 s96, s82, s92
	s_ashr_i32 s77, s76, 31
	s_lshl_b64 s[84:85], s[76:77], 20
	s_add_u32 s84, s24, s84
	s_addc_u32 s85, s26, s85
	s_and_b64 vcc, s[80:81], exec
	s_cselect_b32 s77, s85, s91
	s_cselect_b32 vcc_lo, s84, s90
	s_lshl_b32 s86, s86, 8
	s_ashr_i32 s87, s86, 31
	s_lshl_b64 s[74:75], s[86:87], 2
	s_add_u32 s74, s88, s74
	s_addc_u32 s75, s89, s75
	s_add_i32 m0, s71, s40
	s_add_u32 s88, s92, 0x80080
	global_load_lds_dwordx4 v239, s[74:75]
	s_addc_u32 s89, s93, 0
	s_add_u32 s87, s90, 0x100
	s_addc_u32 vcc_hi, s91, 0
	s_mov_b32 s71, -2
	s_waitcnt vmcnt(0)
	s_add_u32 s67, s88, 0xfff80080
	s_addc_u32 s74, s89, -1
	s_add_i32 s75, 0, 0x10000
	s_cmp_eq_u32 s71, 28
	s_cselect_b32 s93, s79, s74
	s_cselect_b32 s92, s96, s67
	s_cselect_b32 s91, s77, vcc_hi
	s_cselect_b32 s90, vcc_lo, s87
	s_add_i32 s67, 0, 0x14000
	v_add_u32_e32 v96, s75, v238
	v_add_u32_e32 v140, s67, v238
	ds_read_b128 v[64:67], v96
	ds_read_b128 v[72:75], v96 offset:1024
	ds_read_b128 v[88:91], v96 offset:2048
	ds_read_b128 v[96:99], v96 offset:3072
	ds_read_b128 v[108:111], v140
	ds_read_b128 v[116:119], v140 offset:1024
	ds_read_b128 v[128:131], v140 offset:2048
	ds_read_b128 v[140:143], v140 offset:3072
	s_add_i32 m0, s28, 0xc000
	ds_read_b128 v[152:155], v240
	ds_read_b128 v[156:159], v240 offset:1024
	ds_read_b128 v[160:163], v240 offset:2048
	ds_read_b128 v[164:167], v240 offset:3072
	ds_read_b128 v[168:171], v240 offset:4096
	ds_read_b128 v[180:183], v240 offset:5120
	ds_read_b128 v[184:187], v240 offset:6144
	ds_read_b128 v[188:191], v240 offset:7168
	global_load_lds_dwordx4 v230, s[88:89]
	s_add_i32 m0, s28, 0xe000
	s_nop 0
	global_load_lds_dwordx4 v232, s[88:89]
	s_cmp_lg_u32 s94, 1
	s_cbranch_scc1 .Lds4_0
	s_waitcnt vmcnt(8)
.Lds4_0:
	s_waitcnt lgkmcnt(0)
	s_barrier
	s_waitcnt lgkmcnt(0)
	v_mfma_f32_16x16x32_bf16 v[176:179], v[64:67], v[152:155], 0
	v_mfma_f32_16x16x32_bf16 v[176:179], v[72:75], v[156:159], v[176:179]
	v_mfma_f32_16x16x32_bf16 v[148:151], v[108:111], v[152:155], 0
	v_mfma_f32_16x16x32_bf16 v[148:151], v[116:119], v[156:159], v[148:151]
	v_mfma_f32_16x16x32_bf16 v[172:175], v[88:91], v[152:155], 0
	v_mfma_f32_16x16x32_bf16 v[172:175], v[96:99], v[156:159], v[172:175]
	v_mfma_f32_16x16x32_bf16 v[144:147], v[128:131], v[152:155], 0
	v_mfma_f32_16x16x32_bf16 v[144:147], v[140:143], v[156:159], v[144:147]
	v_mfma_f32_16x16x32_bf16 v[136:139], v[64:67], v[160:163], 0
	v_mfma_f32_16x16x32_bf16 v[136:139], v[72:75], v[164:167], v[136:139]
	v_mfma_f32_16x16x32_bf16 v[124:127], v[108:111], v[160:163], 0
	v_mfma_f32_16x16x32_bf16 v[124:127], v[116:119], v[164:167], v[124:127]
	v_mfma_f32_16x16x32_bf16 v[132:135], v[88:91], v[160:163], 0
	v_mfma_f32_16x16x32_bf16 v[132:135], v[96:99], v[164:167], v[132:135]
	v_mfma_f32_16x16x32_bf16 v[120:123], v[128:131], v[160:163], 0
	v_mfma_f32_16x16x32_bf16 v[120:123], v[140:143], v[164:167], v[120:123]
	v_mfma_f32_16x16x32_bf16 v[112:115], v[64:67], v[168:171], 0
	v_mfma_f32_16x16x32_bf16 v[112:115], v[72:75], v[180:183], v[112:115]
	v_mfma_f32_16x16x32_bf16 v[100:103], v[108:111], v[168:171], 0
	v_mfma_f32_16x16x32_bf16 v[100:103], v[116:119], v[180:183], v[100:103]
	v_mfma_f32_16x16x32_bf16 v[104:107], v[88:91], v[168:171], 0
	v_mfma_f32_16x16x32_bf16 v[104:107], v[96:99], v[180:183], v[104:107]
	v_mfma_f32_16x16x32_bf16 v[92:95], v[128:131], v[168:171], 0
	v_mfma_f32_16x16x32_bf16 v[92:95], v[140:143], v[180:183], v[92:95]
	v_mfma_f32_16x16x32_bf16 v[84:87], v[64:67], v[184:187], 0
	v_mfma_f32_16x16x32_bf16 v[84:87], v[72:75], v[188:191], v[84:87]
	v_mfma_f32_16x16x32_bf16 v[76:79], v[108:111], v[184:187], 0
	v_mfma_f32_16x16x32_bf16 v[76:79], v[116:119], v[188:191], v[76:79]
	v_mfma_f32_16x16x32_bf16 v[80:83], v[88:91], v[184:187], 0
	v_mfma_f32_16x16x32_bf16 v[80:83], v[96:99], v[188:191], v[80:83]
	v_mfma_f32_16x16x32_bf16 v[68:71], v[128:131], v[184:187], 0
	v_mfma_f32_16x16x32_bf16 v[68:71], v[140:143], v[188:191], v[68:71]
	s_barrier
	s_add_i32 s74, s75, s2
	s_mov_b32 m0, s74
	ds_read_b128 v[152:155], v240 offset:16384
	ds_read_b128 v[156:159], v240 offset:17408
	ds_read_b128 v[160:163], v240 offset:18432
	ds_read_b128 v[164:167], v240 offset:19456
	ds_read_b128 v[168:171], v240 offset:20480
	ds_read_b128 v[180:183], v240 offset:21504
	ds_read_b128 v[184:187], v240 offset:22528
	ds_read_b128 v[188:191], v240 offset:23552
	global_load_lds_dwordx4 v216, s[90:91]
	s_add_i32 m0, s74, 0x2000
	s_add_u32 s74, s90, 0x80000
	s_addc_u32 s75, s91, 0
	s_add_i32 s67, s67, s2
	global_load_lds_dwordx4 v228, s[90:91]
	s_mov_b32 m0, s67
	s_nop 0
	global_load_lds_dwordx4 v216, s[74:75]
	s_add_i32 m0, s67, 0x2000
	s_nop 0
	global_load_lds_dwordx4 v228, s[74:75]
	s_mov_b32 m0, s28
	s_nop 0
	global_load_lds_dwordx4 v224, s[92:93]
	s_mov_b32 m0, s29
	s_nop 0
	global_load_lds_dwordx4 v226, s[92:93]
	s_cmp_lg_u32 s94, 1
	s_cbranch_scc1 .Lds4_1
	s_waitcnt vmcnt(8)
.Lds4_1:
	s_waitcnt lgkmcnt(0)
	s_barrier
	s_waitcnt lgkmcnt(0)
	v_mfma_f32_16x16x32_bf16 v[60:63], v[64:67], v[152:155], 0
	v_mfma_f32_16x16x32_bf16 v[60:63], v[72:75], v[156:159], v[60:63]
	v_mfma_f32_16x16x32_bf16 v[52:55], v[108:111], v[152:155], 0
	v_mfma_f32_16x16x32_bf16 v[52:55], v[116:119], v[156:159], v[52:55]
	v_mfma_f32_16x16x32_bf16 v[56:59], v[88:91], v[152:155], 0
	v_mfma_f32_16x16x32_bf16 v[56:59], v[96:99], v[156:159], v[56:59]
	v_mfma_f32_16x16x32_bf16 v[48:51], v[128:131], v[152:155], 0
	v_mfma_f32_16x16x32_bf16 v[48:51], v[140:143], v[156:159], v[48:51]
	v_mfma_f32_16x16x32_bf16 v[44:47], v[64:67], v[160:163], 0
	v_mfma_f32_16x16x32_bf16 v[44:47], v[72:75], v[164:167], v[44:47]
	v_mfma_f32_16x16x32_bf16 v[36:39], v[108:111], v[160:163], 0
	v_mfma_f32_16x16x32_bf16 v[36:39], v[116:119], v[164:167], v[36:39]
	v_mfma_f32_16x16x32_bf16 v[40:43], v[88:91], v[160:163], 0
	v_mfma_f32_16x16x32_bf16 v[40:43], v[96:99], v[164:167], v[40:43]
	v_mfma_f32_16x16x32_bf16 v[32:35], v[128:131], v[160:163], 0
	v_mfma_f32_16x16x32_bf16 v[32:35], v[140:143], v[164:167], v[32:35]
	v_mfma_f32_16x16x32_bf16 v[28:31], v[64:67], v[168:171], 0
	v_mfma_f32_16x16x32_bf16 v[28:31], v[72:75], v[180:183], v[28:31]
	v_mfma_f32_16x16x32_bf16 v[20:23], v[108:111], v[168:171], 0
	v_mfma_f32_16x16x32_bf16 v[20:23], v[116:119], v[180:183], v[20:23]
	v_mfma_f32_16x16x32_bf16 v[24:27], v[88:91], v[168:171], 0
	v_mfma_f32_16x16x32_bf16 v[24:27], v[96:99], v[180:183], v[24:27]
	v_mfma_f32_16x16x32_bf16 v[16:19], v[128:131], v[168:171], 0
	v_mfma_f32_16x16x32_bf16 v[16:19], v[140:143], v[180:183], v[16:19]
	v_mfma_f32_16x16x32_bf16 v[12:15], v[64:67], v[184:187], 0
	v_mfma_f32_16x16x32_bf16 v[12:15], v[72:75], v[188:191], v[12:15]
	v_mfma_f32_16x16x32_bf16 v[4:7], v[108:111], v[184:187], 0
	v_mfma_f32_16x16x32_bf16 v[4:7], v[116:119], v[188:191], v[4:7]
	v_mfma_f32_16x16x32_bf16 v[8:11], v[88:91], v[184:187], 0
	v_mfma_f32_16x16x32_bf16 v[8:11], v[96:99], v[188:191], v[8:11]
	v_mfma_f32_16x16x32_bf16 v[0:3], v[128:131], v[184:187], 0
	v_mfma_f32_16x16x32_bf16 v[0:3], v[140:143], v[188:191], v[0:3]
	s_barrier
	s_add_i32 s67, 0, 0x18000
	s_add_i32 s3, 0, 0x1c000
	v_add_u32_e32 v96, s67, v238
	v_add_u32_e32 v140, s3, v238
	ds_read_b128 v[64:67], v96
	ds_read_b128 v[72:75], v96 offset:1024
	ds_read_b128 v[88:91], v96 offset:2048
	ds_read_b128 v[96:99], v96 offset:3072
	ds_read_b128 v[108:111], v140
	ds_read_b128 v[116:119], v140 offset:1024
	ds_read_b128 v[128:131], v140 offset:2048
	ds_read_b128 v[140:143], v140 offset:3072
	s_add_u32 s74, s92, 0x80000
	s_addc_u32 s75, s93, 0
	s_mov_b32 m0, s34
	ds_read_b128 v[152:155], v240 offset:32768
	ds_read_b128 v[156:159], v240 offset:33792
	ds_read_b128 v[160:163], v240 offset:34816
	ds_read_b128 v[164:167], v240 offset:35840
	ds_read_b128 v[168:171], v240 offset:36864
	ds_read_b128 v[180:183], v240 offset:37888
	ds_read_b128 v[184:187], v240 offset:38912
	ds_read_b128 v[188:191], v240 offset:39936
	global_load_lds_dwordx4 v224, s[74:75]
	s_mov_b32 m0, s35
	s_nop 0
	global_load_lds_dwordx4 v226, s[74:75]
	s_waitcnt vmcnt(8)
	s_waitcnt lgkmcnt(0)
	s_barrier
	s_waitcnt lgkmcnt(0)
	v_mfma_f32_16x16x32_bf16 v[176:179], v[64:67], v[152:155], v[176:179]
	v_mfma_f32_16x16x32_bf16 v[176:179], v[72:75], v[156:159], v[176:179]
	v_mfma_f32_16x16x32_bf16 v[148:151], v[108:111], v[152:155], v[148:151]
	v_mfma_f32_16x16x32_bf16 v[148:151], v[116:119], v[156:159], v[148:151]
	v_mfma_f32_16x16x32_bf16 v[172:175], v[88:91], v[152:155], v[172:175]
	v_mfma_f32_16x16x32_bf16 v[172:175], v[96:99], v[156:159], v[172:175]
	v_mfma_f32_16x16x32_bf16 v[144:147], v[128:131], v[152:155], v[144:147]
	v_mfma_f32_16x16x32_bf16 v[144:147], v[140:143], v[156:159], v[144:147]
	v_mfma_f32_16x16x32_bf16 v[136:139], v[64:67], v[160:163], v[136:139]
	v_mfma_f32_16x16x32_bf16 v[136:139], v[72:75], v[164:167], v[136:139]
	v_mfma_f32_16x16x32_bf16 v[124:127], v[108:111], v[160:163], v[124:127]
	v_mfma_f32_16x16x32_bf16 v[124:127], v[116:119], v[164:167], v[124:127]
	v_mfma_f32_16x16x32_bf16 v[132:135], v[88:91], v[160:163], v[132:135]
	v_mfma_f32_16x16x32_bf16 v[132:135], v[96:99], v[164:167], v[132:135]
	v_mfma_f32_16x16x32_bf16 v[120:123], v[128:131], v[160:163], v[120:123]
	v_mfma_f32_16x16x32_bf16 v[120:123], v[140:143], v[164:167], v[120:123]
	v_mfma_f32_16x16x32_bf16 v[112:115], v[64:67], v[168:171], v[112:115]
	v_mfma_f32_16x16x32_bf16 v[112:115], v[72:75], v[180:183], v[112:115]
	v_mfma_f32_16x16x32_bf16 v[100:103], v[108:111], v[168:171], v[100:103]
	v_mfma_f32_16x16x32_bf16 v[100:103], v[116:119], v[180:183], v[100:103]
	v_mfma_f32_16x16x32_bf16 v[104:107], v[88:91], v[168:171], v[104:107]
	v_mfma_f32_16x16x32_bf16 v[104:107], v[96:99], v[180:183], v[104:107]
	v_mfma_f32_16x16x32_bf16 v[92:95], v[128:131], v[168:171], v[92:95]
	v_mfma_f32_16x16x32_bf16 v[92:95], v[140:143], v[180:183], v[92:95]
	v_mfma_f32_16x16x32_bf16 v[84:87], v[64:67], v[184:187], v[84:87]
	v_mfma_f32_16x16x32_bf16 v[84:87], v[72:75], v[188:191], v[84:87]
	v_mfma_f32_16x16x32_bf16 v[76:79], v[108:111], v[184:187], v[76:79]
	v_mfma_f32_16x16x32_bf16 v[76:79], v[116:119], v[188:191], v[76:79]
	v_mfma_f32_16x16x32_bf16 v[80:83], v[88:91], v[184:187], v[80:83]
	v_mfma_f32_16x16x32_bf16 v[80:83], v[96:99], v[188:191], v[80:83]
	v_mfma_f32_16x16x32_bf16 v[68:71], v[128:131], v[184:187], v[68:71]
	v_mfma_f32_16x16x32_bf16 v[68:71], v[140:143], v[188:191], v[68:71]
	s_barrier
	s_add_i32 s67, s67, s2
	s_add_u32 s98, s90, 0x80
	s_addc_u32 s99, s91, 0
	s_mov_b32 m0, s67
	ds_read_b128 v[152:155], v240 offset:49152
	ds_read_b128 v[156:159], v240 offset:50176
	ds_read_b128 v[160:163], v240 offset:51200
	ds_read_b128 v[164:167], v240 offset:52224
	ds_read_b128 v[168:171], v240 offset:53248
	ds_read_b128 v[180:183], v240 offset:54272
	ds_read_b128 v[184:187], v240 offset:55296
	ds_read_b128 v[188:191], v240 offset:56320
	global_load_lds_dwordx4 v216, s[98:99]
	s_add_i32 m0, s67, 0x2000
	s_add_u32 s74, s90, 0x80080
	s_addc_u32 s75, s91, 0
	s_add_i32 s3, s3, s2
	global_load_lds_dwordx4 v228, s[98:99]
	s_mov_b32 m0, s3
	s_nop 0
	global_load_lds_dwordx4 v216, s[74:75]
	s_add_i32 m0, s3, 0x2000
	s_nop 0
	global_load_lds_dwordx4 v228, s[74:75]
	s_add_u32 s98, s92, 0x80
	s_addc_u32 s99, s93, 0
	s_mov_b32 m0, s60
	s_nop 0
	global_load_lds_dwordx4 v224, s[98:99]
	s_mov_b32 m0, s61
	s_nop 0
	global_load_lds_dwordx4 v226, s[98:99]
	s_waitcnt vmcnt(8)
	s_waitcnt lgkmcnt(0)
	s_barrier
	s_waitcnt lgkmcnt(0)
	v_mfma_f32_16x16x32_bf16 v[60:63], v[64:67], v[152:155], v[60:63]
	v_mfma_f32_16x16x32_bf16 v[60:63], v[72:75], v[156:159], v[60:63]
	v_mfma_f32_16x16x32_bf16 v[52:55], v[108:111], v[152:155], v[52:55]
	v_mfma_f32_16x16x32_bf16 v[52:55], v[116:119], v[156:159], v[52:55]
	v_mfma_f32_16x16x32_bf16 v[56:59], v[88:91], v[152:155], v[56:59]
	v_mfma_f32_16x16x32_bf16 v[56:59], v[96:99], v[156:159], v[56:59]
	v_mfma_f32_16x16x32_bf16 v[48:51], v[128:131], v[152:155], v[48:51]
	v_mfma_f32_16x16x32_bf16 v[48:51], v[140:143], v[156:159], v[48:51]
	v_mfma_f32_16x16x32_bf16 v[44:47], v[64:67], v[160:163], v[44:47]
	v_mfma_f32_16x16x32_bf16 v[44:47], v[72:75], v[164:167], v[44:47]
	v_mfma_f32_16x16x32_bf16 v[36:39], v[108:111], v[160:163], v[36:39]
	v_mfma_f32_16x16x32_bf16 v[36:39], v[116:119], v[164:167], v[36:39]
	v_mfma_f32_16x16x32_bf16 v[40:43], v[88:91], v[160:163], v[40:43]
	v_mfma_f32_16x16x32_bf16 v[40:43], v[96:99], v[164:167], v[40:43]
	v_mfma_f32_16x16x32_bf16 v[32:35], v[128:131], v[160:163], v[32:35]
	v_mfma_f32_16x16x32_bf16 v[32:35], v[140:143], v[164:167], v[32:35]
	v_mfma_f32_16x16x32_bf16 v[28:31], v[64:67], v[168:171], v[28:31]
	v_mfma_f32_16x16x32_bf16 v[28:31], v[72:75], v[180:183], v[28:31]
	v_mfma_f32_16x16x32_bf16 v[20:23], v[108:111], v[168:171], v[20:23]
	v_mfma_f32_16x16x32_bf16 v[20:23], v[116:119], v[180:183], v[20:23]
	v_mfma_f32_16x16x32_bf16 v[24:27], v[88:91], v[168:171], v[24:27]
	v_mfma_f32_16x16x32_bf16 v[24:27], v[96:99], v[180:183], v[24:27]
	v_mfma_f32_16x16x32_bf16 v[16:19], v[128:131], v[168:171], v[16:19]
	v_mfma_f32_16x16x32_bf16 v[16:19], v[140:143], v[180:183], v[16:19]
	v_mfma_f32_16x16x32_bf16 v[12:15], v[64:67], v[184:187], v[12:15]
	v_mfma_f32_16x16x32_bf16 v[12:15], v[72:75], v[188:191], v[12:15]
	v_mfma_f32_16x16x32_bf16 v[4:7], v[108:111], v[184:187], v[4:7]
	v_mfma_f32_16x16x32_bf16 v[4:7], v[116:119], v[188:191], v[4:7]
	v_mfma_f32_16x16x32_bf16 v[8:11], v[88:91], v[184:187], v[8:11]
	v_mfma_f32_16x16x32_bf16 v[8:11], v[96:99], v[188:191], v[8:11]
	v_mfma_f32_16x16x32_bf16 v[0:3], v[128:131], v[184:187], v[0:3]
	v_mfma_f32_16x16x32_bf16 v[0:3], v[140:143], v[188:191], v[0:3]
	s_barrier
	s_add_i32 s71, s71, 2
	s_add_u32 s88, s88, 0x100
	s_addc_u32 s89, s89, 0
	s_add_u32 s87, s87, 0x100
	s_addc_u32 vcc_hi, vcc_hi, 0

.LBB0_1289:
	s_lshl_b32 s80, s96, 8
	s_ashr_i32 s81, s80, 31
	s_lshl_b64 s[86:87], s[80:81], 2
	s_add_u32 s84, s84, s86
	s_addc_u32 s85, s85, s87
	s_add_i32 m0, s94, s41
	s_add_u32 s81, s82, 0x100
	global_load_lds_dwordx4 v239, s[84:85]
	s_addc_u32 s96, s83, 0
	s_cmp_eq_u32 s54, 5
	s_cselect_b32 vcc_lo, 66, -2
	s_bfe_u32 s86, s1, 0x20003
	s_cmp_eq_u32 s86, 3
	s_cselect_b32 s86, -8, 0
	s_cmp_eq_u32 s54, 5
	s_cselect_b32 s86, s86, 0
	s_add_i32 vcc_lo, vcc_lo, s86
	s_add_u32 s82, s78, 0x100
	s_addc_u32 s83, s79, 0
	s_add_i32 s94, 0, 0x10000
	s_cmpk_eq_i32 vcc_lo, 0x54
	s_cselect_b32 s87, s75, s83
	s_cselect_b32 s86, s74, s82
	s_cselect_b32 s85, s77, s96
	s_cselect_b32 s84, s76, s81
	s_add_i32 vcc_hi, 0, 0x14000
	v_add_u32_e32 v96, s94, v238
	v_add_u32_e32 v140, vcc_hi, v238
	ds_read_b128 v[64:67], v96
	ds_read_b128 v[72:75], v96 offset:1024
	ds_read_b128 v[88:91], v96 offset:2048
	ds_read_b128 v[96:99], v96 offset:3072
	ds_read_b128 v[108:111], v140
	ds_read_b128 v[116:119], v140 offset:1024
	ds_read_b128 v[128:131], v140 offset:2048
	ds_read_b128 v[140:143], v140 offset:3072
	s_add_i32 m0, s29, 0xc000
	ds_read_b128 v[152:155], v240
	ds_read_b128 v[156:159], v240 offset:1024
	ds_read_b128 v[160:163], v240 offset:2048
	ds_read_b128 v[164:167], v240 offset:3072
	ds_read_b128 v[168:171], v240 offset:4096
	ds_read_b128 v[180:183], v240 offset:5120
	ds_read_b128 v[184:187], v240 offset:6144
	ds_read_b128 v[188:191], v240 offset:7168
	global_load_lds_dwordx4 v230, s[78:79]
	s_add_i32 m0, s29, 0xe000
	s_nop 0
	global_load_lds_dwordx4 v232, s[78:79]
	s_cmp_lg_u32 s54, 1
	s_cbranch_scc1 .Lds6_0
	s_waitcnt vmcnt(8)
.Lds6_0:
	s_waitcnt lgkmcnt(0)
	s_barrier
	s_waitcnt lgkmcnt(0)
	v_mfma_f32_16x16x32_bf16 v[176:179], v[64:67], v[152:155], 0
	v_mfma_f32_16x16x32_bf16 v[176:179], v[72:75], v[156:159], v[176:179]
	v_mfma_f32_16x16x32_bf16 v[148:151], v[108:111], v[152:155], 0
	v_mfma_f32_16x16x32_bf16 v[148:151], v[116:119], v[156:159], v[148:151]
	v_mfma_f32_16x16x32_bf16 v[172:175], v[88:91], v[152:155], 0
	v_mfma_f32_16x16x32_bf16 v[172:175], v[96:99], v[156:159], v[172:175]
	v_mfma_f32_16x16x32_bf16 v[144:147], v[128:131], v[152:155], 0
	v_mfma_f32_16x16x32_bf16 v[144:147], v[140:143], v[156:159], v[144:147]
	v_mfma_f32_16x16x32_bf16 v[136:139], v[64:67], v[160:163], 0
	v_mfma_f32_16x16x32_bf16 v[136:139], v[72:75], v[164:167], v[136:139]
	v_mfma_f32_16x16x32_bf16 v[124:127], v[108:111], v[160:163], 0
	v_mfma_f32_16x16x32_bf16 v[124:127], v[116:119], v[164:167], v[124:127]
	v_mfma_f32_16x16x32_bf16 v[132:135], v[88:91], v[160:163], 0
	v_mfma_f32_16x16x32_bf16 v[132:135], v[96:99], v[164:167], v[132:135]
	v_mfma_f32_16x16x32_bf16 v[120:123], v[128:131], v[160:163], 0
	v_mfma_f32_16x16x32_bf16 v[120:123], v[140:143], v[164:167], v[120:123]
	v_mfma_f32_16x16x32_bf16 v[112:115], v[64:67], v[168:171], 0
	v_mfma_f32_16x16x32_bf16 v[112:115], v[72:75], v[180:183], v[112:115]
	v_mfma_f32_16x16x32_bf16 v[100:103], v[108:111], v[168:171], 0
	v_mfma_f32_16x16x32_bf16 v[100:103], v[116:119], v[180:183], v[100:103]
	v_mfma_f32_16x16x32_bf16 v[104:107], v[88:91], v[168:171], 0
	v_mfma_f32_16x16x32_bf16 v[104:107], v[96:99], v[180:183], v[104:107]
	v_mfma_f32_16x16x32_bf16 v[92:95], v[128:131], v[168:171], 0
	v_mfma_f32_16x16x32_bf16 v[92:95], v[140:143], v[180:183], v[92:95]
	v_mfma_f32_16x16x32_bf16 v[84:87], v[64:67], v[184:187], 0
	v_mfma_f32_16x16x32_bf16 v[84:87], v[72:75], v[188:191], v[84:87]
	v_mfma_f32_16x16x32_bf16 v[76:79], v[108:111], v[184:187], 0
	v_mfma_f32_16x16x32_bf16 v[76:79], v[116:119], v[188:191], v[76:79]
	v_mfma_f32_16x16x32_bf16 v[80:83], v[88:91], v[184:187], 0
	v_mfma_f32_16x16x32_bf16 v[80:83], v[96:99], v[188:191], v[80:83]
	v_mfma_f32_16x16x32_bf16 v[68:71], v[128:131], v[184:187], 0
	v_mfma_f32_16x16x32_bf16 v[68:71], v[140:143], v[188:191], v[68:71]
	s_barrier
	s_add_i32 s78, s94, s2
	s_mov_b32 m0, s78
	ds_read_b128 v[152:155], v240 offset:16384
	ds_read_b128 v[156:159], v240 offset:17408
	ds_read_b128 v[160:163], v240 offset:18432
	ds_read_b128 v[164:167], v240 offset:19456
	ds_read_b128 v[168:171], v240 offset:20480
	ds_read_b128 v[180:183], v240 offset:21504
	ds_read_b128 v[184:187], v240 offset:22528
	ds_read_b128 v[188:191], v240 offset:23552
	global_load_lds_dwordx4 v216, s[84:85]
	s_add_i32 m0, s78, 0x2000
	s_add_u32 s78, s84, 0x160000
	s_addc_u32 s79, s85, 0
	s_add_i32 s94, vcc_hi, s2
	global_load_lds_dwordx4 v228, s[84:85]
	s_mov_b32 m0, s94
	s_nop 0
	global_load_lds_dwordx4 v216, s[78:79]
	s_add_i32 m0, s94, 0x2000
	s_nop 0
	global_load_lds_dwordx4 v228, s[78:79]
	s_mov_b32 m0, s29
	s_nop 0
	global_load_lds_dwordx4 v224, s[86:87]
	s_mov_b32 m0, s34
	s_nop 0
	global_load_lds_dwordx4 v226, s[86:87]
	s_cmp_lg_u32 s54, 1
	s_cbranch_scc1 .Lds6_1
	s_waitcnt vmcnt(8)
.Lds6_1:
	s_waitcnt lgkmcnt(0)
	s_barrier
	s_waitcnt lgkmcnt(0)
	v_mfma_f32_16x16x32_bf16 v[60:63], v[64:67], v[152:155], 0
	v_mfma_f32_16x16x32_bf16 v[60:63], v[72:75], v[156:159], v[60:63]
	v_mfma_f32_16x16x32_bf16 v[52:55], v[108:111], v[152:155], 0
	v_mfma_f32_16x16x32_bf16 v[52:55], v[116:119], v[156:159], v[52:55]
	v_mfma_f32_16x16x32_bf16 v[56:59], v[88:91], v[152:155], 0
	v_mfma_f32_16x16x32_bf16 v[56:59], v[96:99], v[156:159], v[56:59]
	v_mfma_f32_16x16x32_bf16 v[48:51], v[128:131], v[152:155], 0
	v_mfma_f32_16x16x32_bf16 v[48:51], v[140:143], v[156:159], v[48:51]
	v_mfma_f32_16x16x32_bf16 v[44:47], v[64:67], v[160:163], 0
	v_mfma_f32_16x16x32_bf16 v[44:47], v[72:75], v[164:167], v[44:47]
	v_mfma_f32_16x16x32_bf16 v[36:39], v[108:111], v[160:163], 0
	v_mfma_f32_16x16x32_bf16 v[36:39], v[116:119], v[164:167], v[36:39]
	v_mfma_f32_16x16x32_bf16 v[40:43], v[88:91], v[160:163], 0
	v_mfma_f32_16x16x32_bf16 v[40:43], v[96:99], v[164:167], v[40:43]
	v_mfma_f32_16x16x32_bf16 v[32:35], v[128:131], v[160:163], 0
	v_mfma_f32_16x16x32_bf16 v[32:35], v[140:143], v[164:167], v[32:35]
	v_mfma_f32_16x16x32_bf16 v[28:31], v[64:67], v[168:171], 0
	v_mfma_f32_16x16x32_bf16 v[28:31], v[72:75], v[180:183], v[28:31]
	v_mfma_f32_16x16x32_bf16 v[20:23], v[108:111], v[168:171], 0
	v_mfma_f32_16x16x32_bf16 v[20:23], v[116:119], v[180:183], v[20:23]
	v_mfma_f32_16x16x32_bf16 v[24:27], v[88:91], v[168:171], 0
	v_mfma_f32_16x16x32_bf16 v[24:27], v[96:99], v[180:183], v[24:27]
	v_mfma_f32_16x16x32_bf16 v[16:19], v[128:131], v[168:171], 0
	v_mfma_f32_16x16x32_bf16 v[16:19], v[140:143], v[180:183], v[16:19]
	v_mfma_f32_16x16x32_bf16 v[12:15], v[64:67], v[184:187], 0
	v_mfma_f32_16x16x32_bf16 v[12:15], v[72:75], v[188:191], v[12:15]
	v_mfma_f32_16x16x32_bf16 v[4:7], v[108:111], v[184:187], 0
	v_mfma_f32_16x16x32_bf16 v[4:7], v[116:119], v[188:191], v[4:7]
	v_mfma_f32_16x16x32_bf16 v[8:11], v[88:91], v[184:187], 0
	v_mfma_f32_16x16x32_bf16 v[8:11], v[96:99], v[188:191], v[8:11]
	v_mfma_f32_16x16x32_bf16 v[0:3], v[128:131], v[184:187], 0
	v_mfma_f32_16x16x32_bf16 v[0:3], v[140:143], v[188:191], v[0:3]
	s_barrier
	s_add_i32 s94, 0, 0x18000
	s_add_i32 vcc_hi, 0, 0x1c000
	v_add_u32_e32 v96, s94, v238
	v_add_u32_e32 v140, vcc_hi, v238
	ds_read_b128 v[64:67], v96
	ds_read_b128 v[72:75], v96 offset:1024
	ds_read_b128 v[88:91], v96 offset:2048
	ds_read_b128 v[96:99], v96 offset:3072
	ds_read_b128 v[108:111], v140
	ds_read_b128 v[116:119], v140 offset:1024
	ds_read_b128 v[128:131], v140 offset:2048
	ds_read_b128 v[140:143], v140 offset:3072
	s_add_u32 s78, s86, 0x160000
	s_addc_u32 s79, s87, 0
	s_mov_b32 m0, s35
	ds_read_b128 v[152:155], v240 offset:32768
	ds_read_b128 v[156:159], v240 offset:33792
	ds_read_b128 v[160:163], v240 offset:34816
	ds_read_b128 v[164:167], v240 offset:35840
	ds_read_b128 v[168:171], v240 offset:36864
	ds_read_b128 v[180:183], v240 offset:37888
	ds_read_b128 v[184:187], v240 offset:38912
	ds_read_b128 v[188:191], v240 offset:39936
	global_load_lds_dwordx4 v224, s[78:79]
	s_mov_b32 m0, s38
	s_nop 0
	global_load_lds_dwordx4 v226, s[78:79]
	s_waitcnt vmcnt(8)
	s_waitcnt lgkmcnt(0)
	s_barrier
	s_waitcnt lgkmcnt(0)
	v_mfma_f32_16x16x32_bf16 v[176:179], v[64:67], v[152:155], v[176:179]
	v_mfma_f32_16x16x32_bf16 v[176:179], v[72:75], v[156:159], v[176:179]
	v_mfma_f32_16x16x32_bf16 v[148:151], v[108:111], v[152:155], v[148:151]
	v_mfma_f32_16x16x32_bf16 v[148:151], v[116:119], v[156:159], v[148:151]
	v_mfma_f32_16x16x32_bf16 v[172:175], v[88:91], v[152:155], v[172:175]
	v_mfma_f32_16x16x32_bf16 v[172:175], v[96:99], v[156:159], v[172:175]
	v_mfma_f32_16x16x32_bf16 v[144:147], v[128:131], v[152:155], v[144:147]
	v_mfma_f32_16x16x32_bf16 v[144:147], v[140:143], v[156:159], v[144:147]
	v_mfma_f32_16x16x32_bf16 v[136:139], v[64:67], v[160:163], v[136:139]
	v_mfma_f32_16x16x32_bf16 v[136:139], v[72:75], v[164:167], v[136:139]
	v_mfma_f32_16x16x32_bf16 v[124:127], v[108:111], v[160:163], v[124:127]
	v_mfma_f32_16x16x32_bf16 v[124:127], v[116:119], v[164:167], v[124:127]
	v_mfma_f32_16x16x32_bf16 v[132:135], v[88:91], v[160:163], v[132:135]
	v_mfma_f32_16x16x32_bf16 v[132:135], v[96:99], v[164:167], v[132:135]
	v_mfma_f32_16x16x32_bf16 v[120:123], v[128:131], v[160:163], v[120:123]
	v_mfma_f32_16x16x32_bf16 v[120:123], v[140:143], v[164:167], v[120:123]
	v_mfma_f32_16x16x32_bf16 v[112:115], v[64:67], v[168:171], v[112:115]
	v_mfma_f32_16x16x32_bf16 v[112:115], v[72:75], v[180:183], v[112:115]
	v_mfma_f32_16x16x32_bf16 v[100:103], v[108:111], v[168:171], v[100:103]
	v_mfma_f32_16x16x32_bf16 v[100:103], v[116:119], v[180:183], v[100:103]
	v_mfma_f32_16x16x32_bf16 v[104:107], v[88:91], v[168:171], v[104:107]
	v_mfma_f32_16x16x32_bf16 v[104:107], v[96:99], v[180:183], v[104:107]
	v_mfma_f32_16x16x32_bf16 v[92:95], v[128:131], v[168:171], v[92:95]
	v_mfma_f32_16x16x32_bf16 v[92:95], v[140:143], v[180:183], v[92:95]
	v_mfma_f32_16x16x32_bf16 v[84:87], v[64:67], v[184:187], v[84:87]
	v_mfma_f32_16x16x32_bf16 v[84:87], v[72:75], v[188:191], v[84:87]
	v_mfma_f32_16x16x32_bf16 v[76:79], v[108:111], v[184:187], v[76:79]
	v_mfma_f32_16x16x32_bf16 v[76:79], v[116:119], v[188:191], v[76:79]
	v_mfma_f32_16x16x32_bf16 v[80:83], v[88:91], v[184:187], v[80:83]
	v_mfma_f32_16x16x32_bf16 v[80:83], v[96:99], v[188:191], v[80:83]
	v_mfma_f32_16x16x32_bf16 v[68:71], v[128:131], v[184:187], v[68:71]
	v_mfma_f32_16x16x32_bf16 v[68:71], v[140:143], v[188:191], v[68:71]
	s_barrier
	s_add_i32 s78, s94, s2
	s_add_u32 s98, s84, 0x80
	s_addc_u32 s99, s85, 0
	s_mov_b32 m0, s78
	ds_read_b128 v[152:155], v240 offset:49152
	ds_read_b128 v[156:159], v240 offset:50176
	ds_read_b128 v[160:163], v240 offset:51200
	ds_read_b128 v[164:167], v240 offset:52224
	ds_read_b128 v[168:171], v240 offset:53248
	ds_read_b128 v[180:183], v240 offset:54272
	ds_read_b128 v[184:187], v240 offset:55296
	ds_read_b128 v[188:191], v240 offset:56320
	global_load_lds_dwordx4 v216, s[98:99]
	s_add_i32 m0, s78, 0x2000
	s_add_u32 s78, s84, 0x160080
	s_addc_u32 s79, s85, 0
	s_add_i32 s84, vcc_hi, s2
	global_load_lds_dwordx4 v228, s[98:99]
	s_mov_b32 m0, s84
	s_nop 0
	global_load_lds_dwordx4 v216, s[78:79]
	s_add_i32 m0, s84, 0x2000
	s_nop 0
	global_load_lds_dwordx4 v228, s[78:79]
	s_add_u32 s98, s86, 0x80
	s_addc_u32 s99, s87, 0
	s_mov_b32 m0, s60
	s_nop 0
	global_load_lds_dwordx4 v224, s[98:99]
	s_mov_b32 m0, s61
	s_nop 0
	global_load_lds_dwordx4 v226, s[98:99]
	s_waitcnt vmcnt(8)
	s_waitcnt lgkmcnt(0)
	s_barrier
	s_waitcnt lgkmcnt(0)
	v_mfma_f32_16x16x32_bf16 v[60:63], v[64:67], v[152:155], v[60:63]
	v_mfma_f32_16x16x32_bf16 v[60:63], v[72:75], v[156:159], v[60:63]
	v_mfma_f32_16x16x32_bf16 v[52:55], v[108:111], v[152:155], v[52:55]
	v_mfma_f32_16x16x32_bf16 v[52:55], v[116:119], v[156:159], v[52:55]
	v_mfma_f32_16x16x32_bf16 v[56:59], v[88:91], v[152:155], v[56:59]
	v_mfma_f32_16x16x32_bf16 v[56:59], v[96:99], v[156:159], v[56:59]
	v_mfma_f32_16x16x32_bf16 v[48:51], v[128:131], v[152:155], v[48:51]
	v_mfma_f32_16x16x32_bf16 v[48:51], v[140:143], v[156:159], v[48:51]
	v_mfma_f32_16x16x32_bf16 v[44:47], v[64:67], v[160:163], v[44:47]
	v_mfma_f32_16x16x32_bf16 v[44:47], v[72:75], v[164:167], v[44:47]
	v_mfma_f32_16x16x32_bf16 v[36:39], v[108:111], v[160:163], v[36:39]
	v_mfma_f32_16x16x32_bf16 v[36:39], v[116:119], v[164:167], v[36:39]
	v_mfma_f32_16x16x32_bf16 v[40:43], v[88:91], v[160:163], v[40:43]
	v_mfma_f32_16x16x32_bf16 v[40:43], v[96:99], v[164:167], v[40:43]
	v_mfma_f32_16x16x32_bf16 v[32:35], v[128:131], v[160:163], v[32:35]
	v_mfma_f32_16x16x32_bf16 v[32:35], v[140:143], v[164:167], v[32:35]
	v_mfma_f32_16x16x32_bf16 v[28:31], v[64:67], v[168:171], v[28:31]
	v_mfma_f32_16x16x32_bf16 v[28:31], v[72:75], v[180:183], v[28:31]
	v_mfma_f32_16x16x32_bf16 v[20:23], v[108:111], v[168:171], v[20:23]
	v_mfma_f32_16x16x32_bf16 v[20:23], v[116:119], v[180:183], v[20:23]
	v_mfma_f32_16x16x32_bf16 v[24:27], v[88:91], v[168:171], v[24:27]
	v_mfma_f32_16x16x32_bf16 v[24:27], v[96:99], v[180:183], v[24:27]
	v_mfma_f32_16x16x32_bf16 v[16:19], v[128:131], v[168:171], v[16:19]
	v_mfma_f32_16x16x32_bf16 v[16:19], v[140:143], v[180:183], v[16:19]
	v_mfma_f32_16x16x32_bf16 v[12:15], v[64:67], v[184:187], v[12:15]
	v_mfma_f32_16x16x32_bf16 v[12:15], v[72:75], v[188:191], v[12:15]
	v_mfma_f32_16x16x32_bf16 v[4:7], v[108:111], v[184:187], v[4:7]
	v_mfma_f32_16x16x32_bf16 v[4:7], v[116:119], v[188:191], v[4:7]
	v_mfma_f32_16x16x32_bf16 v[8:11], v[88:91], v[184:187], v[8:11]
	v_mfma_f32_16x16x32_bf16 v[8:11], v[96:99], v[188:191], v[8:11]
	v_mfma_f32_16x16x32_bf16 v[0:3], v[128:131], v[184:187], v[0:3]
	v_mfma_f32_16x16x32_bf16 v[0:3], v[140:143], v[188:191], v[0:3]
	s_barrier
	s_add_i32 vcc_lo, vcc_lo, 2
	s_add_u32 s81, s81, 0x100
	s_addc_u32 s96, s96, 0
	s_mov_b64 s[78:79], s[82:83]
